# v17 + conv weights for the next unit issued at the loop end (after stores), top waits vmcnt(13)/(12)
# baseline (speedup 1.0000x reference)
; #define LAS __attribute__((address_space(3)))
; __device__ __forceinline__ void ph_conv_inplace(lds_u8* lds, bf16_t* XT, const float* convw, const bf16_t* halo, int norm_mode) {
;     ...
;     for (int u = blockIdx.x; u < 640 * 48; u += gridDim.x) {
;         const int tt = u / 48, cb = u % 48, cc0 = cb * 128;
;         *(LAS vu4*)(raw + ((tid >> 4) + 2) * 128 + g8 * 8) = pb0; *(LAS vu4*)(raw + ((tid >> 4) + 34) * 128 + g8 * 8) = pb1;
;         if (tid < 64) { const int hr = tid >> 4; *(LAS vu4*)(raw + (hr < 2 ? hr : 64 + hr) * 128 + g8 * 8) = ph; }
;         if (u + (int)gridDim.x < 640 * 48) CONV_FETCH(u + (int)gridDim.x);
;         float cw[5][8];
; #pragma unroll
;         for (int tap = 0; tap < 5; ++tap) load8f(convw + tap * 6144 + cc0 + g8 * 8, cw[tap]);
;     ...
;         { const size_t bs = (((size_t)tt * 768 + cb * 16 + g8) * 64 + (tid >> 4)) * 8; *(vu4*)(XT + bs) = outv[0]; *(vu4*)(XT + bs + 32 * 8) = outv[1]; }
.LBB0_364:
	s_or_b64 exec, exec, s[2:3]
	s_load_dword s30, s[76:77], 0x190
	v_lshlrev_b32_e32 v15, 8, v76
	v_lshl_add_u32 v16, v1, 4, 0
	v_add_u32_e32 v77, v16, v15
	v_lshlrev_b32_e32 v15, 1, v0
	v_lshl_add_u64 v[56:57], s[14:15], 0, v[54:55]
	v_lshlrev_b32_e32 v54, 5, v1
	v_lshlrev_b32_e32 v14, 3, v1
	v_and_or_b32 v15, v15, 64, v76
	s_waitcnt lgkmcnt(0)
	v_lshl_add_u64 v[60:61], s[0:1], 0, v[54:55]
	v_lshlrev_b32_e32 v54, 4, v76
	v_lshl_add_u32 v78, v15, 8, v16
	v_cmp_lt_u32_e64 s[6:7], 31, v0
	v_add_u32_e32 v58, -2, v76
	v_mov_b32_e32 v59, v55
	v_lshl_add_u64 v[62:63], s[14:15], 0, v[54:55]
	s_lshl_b32 s31, s70, 7
	s_lshl_b32 s33, s30, 7
	s_lshl_b32 s34, s70, 4
	s_lshl_b32 s35, s30, 4
	s_movk_i32 s36, 0x6000
	s_movk_i32 s37, 0x2000
	s_movk_i32 s38, 0x3000
	s_mov_b64 s[0:1], 0x6000
	v_lshlrev_b32_e32 v54, 1, v14
	s_mov_b64 s[2:3], 0xc000
	s_mov_b32 s39, 0xc000
	s_mov_b64 s[8:9], 0x12000
	s_mov_b32 s40, 0x12000
	s_mov_b64 s[10:11], 0x18000
	s_mov_b32 s41, 0x18000
	s_mov_b32 s42, 0x800000
	v_mov_b32_e32 v79, 0x3000
	v_mov_b32_e32 v80, 0x3db504f3
	v_mbcnt_lo_u32_b32 v81, -1, 0
	s_mov_b32 s44, s70
	s_mul_hi_i32 s20, s44, 0x2aaaaaab
	s_lshr_b32 s21, s20, 31
	s_ashr_i32 s22, s20, 3
	s_add_i32 s22, s22, s21
	s_mul_i32 s20, s22, 0xffffe800
	s_add_i32 s20, s31, s20
	s_ashr_i32 s21, s20, 31
	v_lshl_add_u64 v[14:15], s[20:21], 2, v[60:61]
	v_add_co_u32_e32 v18, vcc, s36, v14
	v_lshl_add_u64 v[16:17], v[14:15], 0, s[0:1]
	s_nop 0
	v_addc_co_u32_e32 v19, vcc, 0, v15, vcc
	v_add_co_u32_e32 v22, vcc, s39, v14
	global_load_dwordx4 v[34:37], v[14:15], off
	global_load_dwordx4 v[38:41], v[18:19], off
	s_nop 0
	global_load_dwordx4 v[18:21], v[16:17], off offset:16
	v_lshl_add_u64 v[16:17], v[14:15], 0, s[2:3]
	v_addc_co_u32_e32 v23, vcc, 0, v15, vcc
	global_load_dwordx4 v[42:45], v[22:23], off
	s_nop 0
	global_load_dwordx4 v[22:25], v[16:17], off offset:16
	v_lshl_add_u64 v[16:17], v[14:15], 0, s[8:9]
	v_add_co_u32_e32 v46, vcc, s40, v14
	global_load_dwordx4 v[26:29], v[16:17], off offset:16
	s_nop 0
	v_addc_co_u32_e32 v47, vcc, 0, v15, vcc
	v_lshl_add_u64 v[16:17], v[14:15], 0, s[10:11]
	global_load_dwordx4 v[30:33], v[16:17], off offset:16
	global_load_dwordx4 v[50:53], v[46:47], off
	v_add_co_u32_e32 v16, vcc, s41, v14
	s_mul_i32 s46, s22, 0xffffffd0
	s_nop 0
	v_addc_co_u32_e32 v17, vcc, 0, v15, vcc
	global_load_dwordx4 v[46:49], v[16:17], off
	s_nop 0
	global_load_dwordx4 v[14:17], v[14:15], off offset:16
	s_waitcnt vmcnt(0)
	s_branch .LBB0_366
.LBB0_365:
	s_mul_hi_i32 s20, s22, 0x300
	s_mul_i32 s21, s22, 0x300
	s_mulk_i32 s22, 0xfd00
	s_add_i32 s22, s34, s22
	s_ashr_i32 s23, s22, 31
	s_add_u32 s21, s21, s22
	s_addc_u32 s20, s20, s23
	v_cvt_pk_bf16_f32 v27, v14, v15
	v_mov_b32_e32 v15, s20
	v_or_b32_e32 v14, s21, v1
	v_lshlrev_b64 v[14:15], 10, v[14:15]
	v_cvt_pk_bf16_f32 v22, v64, v65
	v_cvt_pk_bf16_f32 v23, v66, v67
	v_cvt_pk_bf16_f32 v24, v68, v69
	v_cvt_pk_bf16_f32 v25, v70, v71
	v_lshl_add_u64 v[14:15], v[62:63], 0, v[14:15]
	v_cvt_pk_bf16_f32 v26, v20, v21
	v_cvt_pk_bf16_f32 v28, v16, v17
	v_cvt_pk_bf16_f32 v29, v18, v19
	global_store_dwordx4 v[14:15], v[22:25], off
	global_store_dwordx4 v[14:15], v[26:29], off offset:512
	v_xor_b32_e32 v77, 0x8000, v77
	v_xor_b32_e32 v78, 0x8000, v78
	s_add_i32 s31, s31, s33
	s_add_i32 s34, s34, s35
	s_andn2_b64 vcc, exec, s[16:17]
	s_mov_b32 s44, s43
	s_cbranch_vccz .LBB0_386
	s_mul_hi_i32 s20, s44, 0x2aaaaaab
	s_lshr_b32 s21, s20, 31
	s_ashr_i32 s22, s20, 3
	s_add_i32 s22, s22, s21
	s_mul_i32 s20, s22, 0xffffe800
	s_add_i32 s20, s31, s20
	s_ashr_i32 s21, s20, 31
	v_lshl_add_u64 v[14:15], s[20:21], 2, v[60:61]
	v_add_co_u32_e32 v18, vcc, s36, v14
	v_lshl_add_u64 v[16:17], v[14:15], 0, s[0:1]
	s_nop 0
	v_addc_co_u32_e32 v19, vcc, 0, v15, vcc
	v_add_co_u32_e32 v22, vcc, s39, v14
	global_load_dwordx4 v[34:37], v[14:15], off
	global_load_dwordx4 v[38:41], v[18:19], off
	s_nop 0
	global_load_dwordx4 v[18:21], v[16:17], off offset:16
	v_lshl_add_u64 v[16:17], v[14:15], 0, s[2:3]
	v_addc_co_u32_e32 v23, vcc, 0, v15, vcc
	global_load_dwordx4 v[42:45], v[22:23], off
	s_nop 0
	global_load_dwordx4 v[22:25], v[16:17], off offset:16
	v_lshl_add_u64 v[16:17], v[14:15], 0, s[8:9]
	v_add_co_u32_e32 v46, vcc, s40, v14
	global_load_dwordx4 v[26:29], v[16:17], off offset:16
	s_nop 0
	v_addc_co_u32_e32 v47, vcc, 0, v15, vcc
	v_lshl_add_u64 v[16:17], v[14:15], 0, s[10:11]
	global_load_dwordx4 v[30:33], v[16:17], off offset:16
	global_load_dwordx4 v[50:53], v[46:47], off
	v_add_co_u32_e32 v16, vcc, s41, v14
	s_mul_i32 s46, s22, 0xffffffd0
	s_nop 0
	v_addc_co_u32_e32 v17, vcc, 0, v15, vcc
	global_load_dwordx4 v[46:49], v[16:17], off
	s_nop 0
	global_load_dwordx4 v[14:17], v[14:15], off offset:16
.LBB0_366:
	s_waitcnt vmcnt(13)
	ds_write_b128 v77, v[2:5] offset:512
	s_waitcnt vmcnt(12)
	ds_write_b128 v77, v[6:9] offset:8704
	s_and_saveexec_b64 s[16:17], s[4:5]
	ds_write_b128 v78, v[10:13]
	s_or_b64 exec, exec, s[16:17]
	s_add_i32 s43, s44, s30
	s_cmpk_gt_i32 s43, 0x77ff
	s_cselect_b64 s[16:17], -1, 0
	s_and_b64 vcc, exec, s[16:17]
	s_cbranch_vccnz .Lconv3_dummy
	s_mul_hi_i32 s20, s43, 0x2aaaaaab
	s_lshr_b32 s21, s20, 31
	s_ashr_i32 s20, s20, 3
	s_add_i32 s22, s20, s21
	s_mul_i32 s23, s22, 0xfffffd00
	s_add_i32 s24, s35, s34
	s_add_i32 s24, s24, s23
	s_mul_i32 s21, s22, 0x300
	s_ashr_i32 s23, s24, 31
	s_mul_hi_i32 s20, s22, 0x300
	s_add_u32 s21, s21, s24
	s_addc_u32 s20, s20, s23
	v_mov_b32_e32 v3, s20
	v_or_b32_e32 v2, s21, v1
	v_lshlrev_b64 v[2:3], 10, v[2:3]
	v_lshl_add_u64 v[6:7], v[56:57], 0, v[2:3]
	global_load_dwordx4 v[2:5], v[6:7], off
	s_nop 0
	global_load_dwordx4 v[6:9], v[6:7], off offset:512
	s_and_saveexec_b64 s[20:21], s[4:5]
	s_cbranch_execz .LBB0_381
	s_lshl_b32 s23, s22, 6
	s_add_i32 s25, s23, 0xffff8000
	s_lshr_b32 s25, s25, 12
	s_ashr_i32 s24, s22, 7
	s_add_i32 s25, s25, 4
	s_cmpk_lt_i32 s43, 0x6000
	s_cselect_b32 s24, s24, s25
	s_lshl_b32 s25, s24, 12
	s_lshl_b32 s26, s24, 13
	s_add_i32 s27, s25, 0x4000
	s_cmp_lt_i32 s24, 4
	s_cselect_b64 s[28:29], -1, 0
	s_and_b64 s[24:25], s[28:29], exec
	s_cselect_b32 s24, s26, s27
	s_sub_i32 s45, s23, s24
	s_mov_b64 s[24:25], 0
	s_and_saveexec_b64 s[26:27], s[6:7]
	s_xor_b64 s[26:27], exec, s[26:27]
	s_cbranch_execz .LBB0_374
	s_add_i32 s23, s45, 64
	s_and_b64 s[24:25], s[28:29], exec
	s_cselect_b32 s24, s37, 0x1000
	s_cmp_lt_i32 s23, s24
	s_mov_b64 s[24:25], 0
	s_cbranch_scc0 .LBB0_373
	s_ashr_i32 s23, s22, 31
	s_lshl_b64 s[24:25], s[22:23], 2
	s_add_u32 s24, s24, 4
	s_addc_u32 s25, s25, 0
	v_lshl_add_u64 v[10:11], s[24:25], 0, v[58:59]
	v_mov_b64_e32 v[12:13], s[18:19]
	v_mad_u64_u32 v[122:123], s[24:25], v10, s38, v[12:13]
	v_mad_i32_i24 v123, v11, s38, v123
	s_mov_b64 s[24:25], -1

; #define LAS __attribute__((address_space(3)))
; __device__ __forceinline__ void ph_conv_inplace(lds_u8* lds, bf16_t* XT, const float* convw, const bf16_t* halo, int norm_mode) {
;     LAS bf16_t* raw = (LAS bf16_t*)lds;
;     const int tid = threadIdx.x, g8 = tid & 15;
;     vu4 pb0, pb1, ph = (vu4){0u, 0u, 0u, 0u};
;     ...
;     if ((int)blockIdx.x < 640 * 48) CONV_FETCH((int)blockIdx.x);
;     for (int u = blockIdx.x; u < 640 * 48; u += gridDim.x) {
;         const int tt = u / 48, cb = u % 48, cc0 = cb * 128;
;         *(LAS vu4*)(raw + ((tid >> 4) + 2) * 128 + g8 * 8) = pb0; *(LAS vu4*)(raw + ((tid >> 4) + 34) * 128 + g8 * 8) = pb1;
;         if (tid < 64) { const int hr = tid >> 4; *(LAS vu4*)(raw + (hr < 2 ? hr : 64 + hr) * 128 + g8 * 8) = ph; }
;         if (u + (int)gridDim.x < 640 * 48) CONV_FETCH(u + (int)gridDim.x);
;         float cw[5][8];
; #pragma unroll
;         for (int tap = 0; tap < 5; ++tap) load8f(convw + tap * 6144 + cc0 + g8 * 8, cw[tap]);
.LBB0_1999:
	s_or_b64 exec, exec, s[2:3]
	s_load_dword s26, s[76:77], 0x190
	v_readlane_b32 s2, v254, 10
	v_lshlrev_b32_e32 v15, 8, v72
	v_lshl_add_u32 v16, v1, 4, 0
	v_readlane_b32 s3, v254, 11
	v_add_u32_e32 v73, v16, v15
	v_lshlrev_b32_e32 v15, 1, v0
	v_lshl_add_u64 v[64:65], s[2:3], 0, v[62:63]
	v_lshlrev_b32_e32 v62, 5, v1
	v_lshlrev_b32_e32 v14, 3, v1
	v_and_or_b32 v15, v15, 64, v72
	s_waitcnt lgkmcnt(0)
	v_lshl_add_u64 v[68:69], s[0:1], 0, v[62:63]
	v_lshlrev_b32_e32 v62, 4, v72
	v_lshl_add_u32 v74, v15, 8, v16
	v_cmp_lt_u32_e64 s[6:7], 31, v0
	v_add_u32_e32 v66, -2, v72
	v_mov_b32_e32 v67, v63
	v_lshl_add_u64 v[70:71], s[2:3], 0, v[62:63]
	s_lshl_b32 s27, s70, 7
	s_lshl_b32 s28, s26, 7
	s_lshl_b32 s37, s70, 4
	s_lshl_b32 s29, s26, 4
	s_movk_i32 s30, 0x6000
	s_movk_i32 s31, 0x2000
	s_movk_i32 s33, 0x3000
	s_mov_b64 s[0:1], 0x6000
	v_lshlrev_b32_e32 v62, 1, v14
	s_mov_b64 s[2:3], 0xc000
	s_mov_b32 s34, 0xc000
	s_mov_b64 s[8:9], 0x12000
	s_mov_b32 s35, 0x12000
	s_mov_b64 s[10:11], 0x18000
	s_mov_b32 s36, 0x18000
	v_mov_b32_e32 v75, 0x3000
	s_mov_b32 s40, s70
	s_mul_hi_i32 s42, s40, 0x2aaaaaab
	s_lshr_b32 s43, s42, 31
	s_ashr_i32 s42, s42, 3
	s_add_i32 s42, s42, s43
	s_mul_i32 s43, s42, 0xffffe800
	s_add_i32 s44, s27, s43
	s_ashr_i32 s45, s44, 31
	v_lshl_add_u64 v[22:23], s[44:45], 2, v[68:69]
	v_add_co_u32_e32 v20, vcc, s30, v22
	v_lshl_add_u64 v[18:19], v[22:23], 0, s[0:1]
	s_nop 0
	v_addc_co_u32_e32 v21, vcc, 0, v23, vcc
	v_add_co_u32_e32 v24, vcc, s34, v22
	global_load_dwordx4 v[14:17], v[22:23], off offset:16
	global_load_dwordx4 v[34:37], v[22:23], off
	v_addc_co_u32_e32 v25, vcc, 0, v23, vcc
	global_load_dwordx4 v[38:41], v[20:21], off
	s_nop 0
	global_load_dwordx4 v[18:21], v[18:19], off offset:16
	s_mul_hi_i32 s43, s42, 0x300
	global_load_dwordx4 v[42:45], v[24:25], off
	v_add_co_u32_e32 v24, vcc, s35, v22
	s_mul_i32 s44, s42, 0x300
	s_nop 0
	v_addc_co_u32_e32 v25, vcc, 0, v23, vcc
	global_load_dwordx4 v[46:49], v[24:25], off
	v_add_co_u32_e32 v24, vcc, s36, v22
	s_mulk_i32 s42, 0xfd00
	s_nop 0
	v_addc_co_u32_e32 v25, vcc, 0, v23, vcc
	global_load_dwordx4 v[50:53], v[24:25], off
	v_lshl_add_u64 v[24:25], v[22:23], 0, s[2:3]
	global_load_dwordx4 v[30:33], v[24:25], off offset:16
	v_lshl_add_u64 v[24:25], v[22:23], 0, s[8:9]
	global_load_dwordx4 v[26:29], v[24:25], off offset:16
	v_lshl_add_u64 v[22:23], v[22:23], 0, s[10:11]
	global_load_dwordx4 v[22:25], v[22:23], off offset:16
	s_waitcnt vmcnt(0)
	s_branch .LBB0_2003

; #define LAS __attribute__((address_space(3)))
; #define LDS_SYNC() do { asm volatile("s_waitcnt lgkmcnt(0)" ::: "memory"); __builtin_amdgcn_s_barrier(); asm volatile("" ::: "memory"); } while (0)
; __device__ __forceinline__ vu4 pack8(const float (&f)[8]) { vu4 w; w.x = pg8::cvt_pk_bf16(f[0], f[1]); w.y = pg8::cvt_pk_bf16(f[2], f[3]); w.z = pg8::cvt_pk_bf16(f[4], f[5]); w.w = pg8::cvt_pk_bf16(f[6], f[7]); return w; }
; __device__ __forceinline__ float silu_f(float x) { return x * __builtin_amdgcn_rcpf(1.0f + __expf(-x)); }
; __device__ __forceinline__ void ph_conv_inplace(lds_u8* lds, bf16_t* XT, const float* convw, const bf16_t* halo, int norm_mode) {
;     ...
;         LDS_SYNC();
;         vu4 outv[2];
; #pragma unroll
;         for (int i = 0; i < 2; ++i) { const int r = (tid >> 4) + 32 * i; float acc[8];
; #pragma unroll
;             for (int j = 0; j < 8; ++j) acc[j] = 0.f;
; #pragma unroll
;             for (int tap = 0; tap < 5; ++tap) { float xv[8]; unpack8(*(const LAS vu4*)(raw + (r + tap) * 128 + g8 * 8), xv);
; #pragma unroll
;                 for (int j = 0; j < 8; ++j) acc[j] += cw[tap][j] * xv[j]; }
;             float ss = 0.f;
; #pragma unroll
;             for (int j = 0; j < 8; ++j) { acc[j] = silu_f(acc[j]); ss += acc[j] * acc[j]; }
;             if (norm_mode == 1 && cb < 32) { ss += __shfl_xor(ss, 1); ss += __shfl_xor(ss, 2); ss += __shfl_xor(ss, 4); ss += __shfl_xor(ss, 8);
;                 const float sc = rsqrtf(ss + EPSN) * (cb < 16 ? 0.08838834764831845f : 1.0f);
; #pragma unroll
;                 for (int j = 0; j < 8; ++j) acc[j] *= sc; }
;             outv[i] = pack8(acc); }
.LBB0_2002:
	s_waitcnt lgkmcnt(0)
	s_barrier
	ds_read_b128 v[76:79], v73
	ds_read_b128 v[80:83], v73 offset:256
	ds_read_b128 v[84:87], v73 offset:512
	ds_read_b128 v[58:61], v73 offset:768
	ds_read_b128 v[54:57], v73 offset:1024
	ds_read_b128 v[88:91], v73 offset:8192
	s_waitcnt lgkmcnt(5)
	v_lshlrev_b32_e32 v92, 16, v76
	v_and_b32_e32 v93, 0xffff0000, v76
	v_lshlrev_b32_e32 v76, 16, v77
	v_and_b32_e32 v77, 0xffff0000, v77
	s_waitcnt lgkmcnt(4)
	v_lshlrev_b32_e32 v94, 16, v80
	v_and_b32_e32 v95, 0xffff0000, v80
	v_lshlrev_b32_e32 v80, 16, v81
	v_and_b32_e32 v81, 0xffff0000, v81
	s_waitcnt lgkmcnt(3)
	v_lshlrev_b32_e32 v96, 16, v84
	v_and_b32_e32 v97, 0xffff0000, v84
	v_lshlrev_b32_e32 v84, 16, v85
	v_and_b32_e32 v85, 0xffff0000, v85
	s_waitcnt lgkmcnt(2)
	v_lshlrev_b32_e32 v98, 16, v58
	v_and_b32_e32 v99, 0xffff0000, v58
	v_lshlrev_b32_e32 v58, 16, v59
	v_and_b32_e32 v59, 0xffff0000, v59
	s_waitcnt lgkmcnt(1)
	v_lshlrev_b32_e32 v100, 16, v54
	v_and_b32_e32 v101, 0xffff0000, v54
	v_lshlrev_b32_e32 v54, 16, v55
	v_and_b32_e32 v55, 0xffff0000, v55
	v_lshlrev_b32_e32 v102, 16, v78
	v_and_b32_e32 v103, 0xffff0000, v78
	v_lshlrev_b32_e32 v104, 16, v82
	v_and_b32_e32 v105, 0xffff0000, v82
	v_lshlrev_b32_e32 v106, 16, v86
	v_and_b32_e32 v107, 0xffff0000, v86
	s_add_i32 s42, s37, s42
	s_ashr_i32 s45, s42, 31
	s_add_u32 s42, s44, s42
	s_addc_u32 s43, s43, s45
	s_add_i32 s27, s27, s28
	s_andn2_b64 vcc, exec, s[12:13]
	s_mov_b32 s37, s39
	s_mov_b32 s40, s38
	s_waitcnt vmcnt(11)
	v_pk_fma_f32 v[102:103], v[14:15], v[102:103], 0 op_sel_hi:[1,1,0]
	s_waitcnt vmcnt(10)
	v_pk_fma_f32 v[76:77], v[36:37], v[76:77], 0 op_sel_hi:[1,1,0]
	v_pk_fma_f32 v[92:93], v[34:35], v[92:93], 0 op_sel_hi:[1,1,0]
	s_waitcnt vmcnt(9)
	v_pk_fma_f32 v[76:77], v[40:41], v[80:81], v[76:77]
	v_pk_fma_f32 v[92:93], v[38:39], v[94:95], v[92:93]
	s_waitcnt vmcnt(8)
	v_pk_fma_f32 v[80:81], v[18:19], v[104:105], v[102:103]
	s_waitcnt vmcnt(7)
	v_pk_fma_f32 v[76:77], v[44:45], v[84:85], v[76:77]
	v_pk_fma_f32 v[92:93], v[42:43], v[96:97], v[92:93]
	s_waitcnt lgkmcnt(0)
	v_lshlrev_b32_e32 v94, 16, v88
	v_and_b32_e32 v95, 0xffff0000, v88
	v_pk_fma_f32 v[34:35], v[34:35], v[94:95], 0 op_sel_hi:[1,1,0]
	s_waitcnt vmcnt(6)
	v_pk_fma_f32 v[58:59], v[48:49], v[58:59], v[76:77]
	v_pk_fma_f32 v[84:85], v[46:47], v[98:99], v[92:93]
	v_lshlrev_b32_e32 v92, 16, v60
	v_and_b32_e32 v93, 0xffff0000, v60
	s_waitcnt vmcnt(5)
	v_pk_fma_f32 v[54:55], v[52:53], v[54:55], v[58:59]
	s_nop 0
	v_mul_f32_e32 v78, 0xbfb8aa3b, v54
	v_mul_f32_e32 v82, 0xbfb8aa3b, v55
	v_exp_f32_e32 v78, v78
	s_waitcnt vmcnt(4)
	v_pk_fma_f32 v[80:81], v[30:31], v[106:107], v[80:81]
	v_exp_f32_e32 v82, v82
	s_waitcnt vmcnt(3)
	v_pk_fma_f32 v[80:81], v[26:27], v[92:93], v[80:81]
	v_lshlrev_b32_e32 v92, 16, v56
	v_and_b32_e32 v93, 0xffff0000, v56
	s_waitcnt vmcnt(2)
	v_pk_fma_f32 v[80:81], v[22:23], v[92:93], v[80:81]
	v_add_f32_e32 v78, 1.0, v78
	v_mul_f32_e32 v60, 0xbfb8aa3b, v81
	v_exp_f32_e32 v60, v60
	v_pk_fma_f32 v[76:77], v[50:51], v[100:101], v[84:85]
	v_add_f32_e32 v82, 1.0, v82
	v_rcp_f32_e32 v84, v78
	v_lshlrev_b32_e32 v78, 16, v79
	v_and_b32_e32 v79, 0xffff0000, v79
	v_rcp_f32_e32 v85, v82
	v_pk_fma_f32 v[78:79], v[16:17], v[78:79], 0 op_sel_hi:[1,1,0]
	v_lshlrev_b32_e32 v82, 16, v83
	v_and_b32_e32 v83, 0xffff0000, v83
	v_pk_fma_f32 v[78:79], v[20:21], v[82:83], v[78:79]
	v_lshlrev_b32_e32 v82, 16, v87
	v_and_b32_e32 v83, 0xffff0000, v87
	v_add_f32_e32 v86, 1.0, v60
	v_pk_fma_f32 v[78:79], v[32:33], v[82:83], v[78:79]
	v_lshlrev_b32_e32 v60, 16, v61
	v_and_b32_e32 v61, 0xffff0000, v61
	v_pk_fma_f32 v[60:61], v[28:29], v[60:61], v[78:79]
	v_lshlrev_b32_e32 v78, 16, v57
	v_and_b32_e32 v79, 0xffff0000, v57
	v_pk_fma_f32 v[60:61], v[24:25], v[78:79], v[60:61]
	v_mul_f32_e32 v58, 0xbfb8aa3b, v76
	v_mul_f32_e32 v59, 0xbfb8aa3b, v77
	v_mul_f32_e32 v57, 0xbfb8aa3b, v60
	v_exp_f32_e32 v58, v58
	v_exp_f32_e32 v59, v59
	v_mul_f32_e32 v56, 0xbfb8aa3b, v80
	v_exp_f32_e32 v78, v57
	v_mul_f32_e32 v57, 0xbfb8aa3b, v61
	v_exp_f32_e32 v56, v56
	v_exp_f32_e32 v79, v57
	v_add_f32_e32 v58, 1.0, v58
	v_add_f32_e32 v59, 1.0, v59
	v_rcp_f32_e32 v58, v58
	v_rcp_f32_e32 v59, v59
	v_add_f32_e32 v56, 1.0, v56
	v_add_f32_e32 v78, 1.0, v78
	v_add_f32_e32 v79, 1.0, v79
	v_rcp_f32_e32 v56, v56
	v_rcp_f32_e32 v57, v86
	v_rcp_f32_e32 v78, v78
	v_rcp_f32_e32 v79, v79
	v_pk_mul_f32 v[58:59], v[76:77], v[58:59]
	v_pk_mul_f32 v[76:77], v[54:55], v[84:85]
	v_pk_mul_f32 v[56:57], v[80:81], v[56:57]
	v_pk_mul_f32 v[92:93], v[60:61], v[78:79]
	v_cvt_pk_bf16_f32 v54, v58, v59
	v_cvt_pk_bf16_f32 v55, v76, v77
	ds_read_b128 v[58:61], v73 offset:8448
	ds_read_b128 v[76:79], v73 offset:8704
	ds_read_b128 v[80:83], v73 offset:8960
	ds_read_b128 v[84:87], v73 offset:9216
	v_cvt_pk_bf16_f32 v56, v56, v57
	s_waitcnt lgkmcnt(3)
	v_lshlrev_b32_e32 v94, 16, v58
	v_and_b32_e32 v95, 0xffff0000, v58
	v_pk_fma_f32 v[34:35], v[38:39], v[94:95], v[34:35]
	s_waitcnt lgkmcnt(2)
; #define LAS __attribute__((address_space(3)))
; __device__ __forceinline__ vu4 pack8(const float (&f)[8]) { vu4 w; w.x = pg8::cvt_pk_bf16(f[0], f[1]); w.y = pg8::cvt_pk_bf16(f[2], f[3]); w.z = pg8::cvt_pk_bf16(f[4], f[5]); w.w = pg8::cvt_pk_bf16(f[6], f[7]); return w; }
; __device__ __forceinline__ float silu_f(float x) { return x * __builtin_amdgcn_rcpf(1.0f + __expf(-x)); }
; __device__ __forceinline__ void ph_conv_inplace(lds_u8* lds, bf16_t* XT, const float* convw, const bf16_t* halo, int norm_mode) {
;     ...
;         *(LAS vu4*)(raw + ((tid >> 4) + 2) * 128 + g8 * 8) = pb0; *(LAS vu4*)(raw + ((tid >> 4) + 34) * 128 + g8 * 8) = pb1;
;         if (tid < 64) { const int hr = tid >> 4; *(LAS vu4*)(raw + (hr < 2 ? hr : 64 + hr) * 128 + g8 * 8) = ph; }
;         if (u + (int)gridDim.x < 640 * 48) CONV_FETCH(u + (int)gridDim.x);
;         float cw[5][8];
; #pragma unroll
;         for (int tap = 0; tap < 5; ++tap) load8f(convw + tap * 6144 + cc0 + g8 * 8, cw[tap]);
;     ...
;             for (int tap = 0; tap < 5; ++tap) { float xv[8]; unpack8(*(const LAS vu4*)(raw + (r + tap) * 128 + g8 * 8), xv);
; #pragma unroll
;                 for (int j = 0; j < 8; ++j) acc[j] += cw[tap][j] * xv[j]; }
;             float ss = 0.f;
; #pragma unroll
;             for (int j = 0; j < 8; ++j) { acc[j] = silu_f(acc[j]); ss += acc[j] * acc[j]; }
;             if (norm_mode == 1 && cb < 32) { ss += __shfl_xor(ss, 1); ss += __shfl_xor(ss, 2); ss += __shfl_xor(ss, 4); ss += __shfl_xor(ss, 8);
;                 const float sc = rsqrtf(ss + EPSN) * (cb < 16 ? 0.08838834764831845f : 1.0f);
; #pragma unroll
;                 for (int j = 0; j < 8; ++j) acc[j] *= sc; }
;             outv[i] = pack8(acc); }
;         { const size_t bs = (((size_t)tt * 768 + cb * 16 + g8) * 64 + (tid >> 4)) * 8; *(vu4*)(XT + bs) = outv[0]; *(vu4*)(XT + bs + 32 * 8) = outv[1]; }
	v_lshlrev_b32_e32 v38, 16, v76
	v_and_b32_e32 v39, 0xffff0000, v76
	v_pk_fma_f32 v[34:35], v[42:43], v[38:39], v[34:35]
	v_lshlrev_b32_e32 v42, 16, v89
	v_and_b32_e32 v43, 0xffff0000, v89
	v_pk_fma_f32 v[36:37], v[36:37], v[42:43], 0 op_sel_hi:[1,1,0]
	v_lshlrev_b32_e32 v42, 16, v59
	v_and_b32_e32 v43, 0xffff0000, v59
	v_pk_fma_f32 v[36:37], v[40:41], v[42:43], v[36:37]
	v_lshlrev_b32_e32 v42, 16, v90
	v_and_b32_e32 v43, 0xffff0000, v90
	v_pk_fma_f32 v[14:15], v[14:15], v[42:43], 0 op_sel_hi:[1,1,0]
	v_lshlrev_b32_e32 v42, 16, v60
	v_and_b32_e32 v43, 0xffff0000, v60
	v_pk_fma_f32 v[14:15], v[18:19], v[42:43], v[14:15]
	v_lshlrev_b32_e32 v18, 16, v78
	v_and_b32_e32 v19, 0xffff0000, v78
	v_pk_fma_f32 v[14:15], v[30:31], v[18:19], v[14:15]
	s_waitcnt lgkmcnt(1)
	v_lshlrev_b32_e32 v18, 16, v82
	v_and_b32_e32 v19, 0xffff0000, v82
	v_pk_fma_f32 v[14:15], v[26:27], v[18:19], v[14:15]
	s_waitcnt lgkmcnt(0)
	v_lshlrev_b32_e32 v18, 16, v86
	v_and_b32_e32 v19, 0xffff0000, v86
	v_pk_fma_f32 v[14:15], v[22:23], v[18:19], v[14:15]
	v_lshlrev_b32_e32 v22, 16, v91
	v_and_b32_e32 v23, 0xffff0000, v91
	v_pk_fma_f32 v[16:17], v[16:17], v[22:23], 0 op_sel_hi:[1,1,0]
	v_lshlrev_b32_e32 v22, 16, v61
	v_and_b32_e32 v23, 0xffff0000, v61
	v_pk_fma_f32 v[16:17], v[20:21], v[22:23], v[16:17]
	v_lshlrev_b32_e32 v20, 16, v79
	v_and_b32_e32 v21, 0xffff0000, v79
	v_pk_fma_f32 v[16:17], v[32:33], v[20:21], v[16:17]
	v_lshlrev_b32_e32 v20, 16, v83
	v_and_b32_e32 v21, 0xffff0000, v83
	v_lshlrev_b32_e32 v40, 16, v77
	v_and_b32_e32 v41, 0xffff0000, v77
	v_pk_fma_f32 v[16:17], v[28:29], v[20:21], v[16:17]
	v_lshlrev_b32_e32 v20, 16, v87
	v_and_b32_e32 v21, 0xffff0000, v87
	v_lshlrev_b32_e32 v38, 16, v80
	v_and_b32_e32 v39, 0xffff0000, v80
	v_pk_fma_f32 v[36:37], v[44:45], v[40:41], v[36:37]
	v_lshlrev_b32_e32 v40, 16, v81
	v_and_b32_e32 v41, 0xffff0000, v81
	v_mul_f32_e32 v18, 0xbfb8aa3b, v14
	v_mul_f32_e32 v19, 0xbfb8aa3b, v15
	v_pk_fma_f32 v[16:17], v[24:25], v[20:21], v[16:17]
	v_pk_fma_f32 v[34:35], v[46:47], v[38:39], v[34:35]
	v_lshlrev_b32_e32 v38, 16, v84
	v_and_b32_e32 v39, 0xffff0000, v84
	v_pk_fma_f32 v[36:37], v[48:49], v[40:41], v[36:37]
	v_lshlrev_b32_e32 v40, 16, v85
	v_and_b32_e32 v41, 0xffff0000, v85
	v_exp_f32_e32 v18, v18
	v_exp_f32_e32 v19, v19
	v_mul_f32_e32 v20, 0xbfb8aa3b, v16
	v_mul_f32_e32 v21, 0xbfb8aa3b, v17
	v_pk_fma_f32 v[34:35], v[50:51], v[38:39], v[34:35]
	v_pk_fma_f32 v[36:37], v[52:53], v[40:41], v[36:37]
	v_exp_f32_e32 v20, v20
	v_exp_f32_e32 v21, v21
	v_mul_f32_e32 v38, 0xbfb8aa3b, v34
	v_mul_f32_e32 v39, 0xbfb8aa3b, v35
	v_mul_f32_e32 v40, 0xbfb8aa3b, v36
	v_mul_f32_e32 v41, 0xbfb8aa3b, v37
	v_exp_f32_e32 v38, v38
	v_exp_f32_e32 v39, v39
	v_exp_f32_e32 v40, v40
	v_exp_f32_e32 v41, v41
	v_add_f32_e32 v18, 1.0, v18
	v_add_f32_e32 v19, 1.0, v19
	v_rcp_f32_e32 v18, v18
	v_rcp_f32_e32 v19, v19
	v_add_f32_e32 v20, 1.0, v20
	v_add_f32_e32 v21, 1.0, v21
	v_rcp_f32_e32 v20, v20
	v_rcp_f32_e32 v21, v21
	v_add_f32_e32 v38, 1.0, v38
	v_add_f32_e32 v39, 1.0, v39
	v_add_f32_e32 v40, 1.0, v40
	v_add_f32_e32 v41, 1.0, v41
	v_rcp_f32_e32 v38, v38
	v_rcp_f32_e32 v39, v39
	v_rcp_f32_e32 v40, v40
	v_rcp_f32_e32 v41, v41
	v_pk_mul_f32 v[18:19], v[14:15], v[18:19]
	v_pk_mul_f32 v[20:21], v[16:17], v[20:21]
	v_cvt_pk_bf16_f32 v16, v18, v19
	v_mov_b32_e32 v19, s43
	v_or_b32_e32 v18, s42, v1
	v_lshlrev_b64 v[18:19], 10, v[18:19]
	v_cvt_pk_bf16_f32 v57, v92, v93
	v_pk_mul_f32 v[22:23], v[34:35], v[38:39]
	v_pk_mul_f32 v[24:25], v[36:37], v[40:41]
	v_lshl_add_u64 v[18:19], v[70:71], 0, v[18:19]
	v_cvt_pk_bf16_f32 v14, v22, v23
	v_cvt_pk_bf16_f32 v15, v24, v25
	v_cvt_pk_bf16_f32 v17, v20, v21
	global_store_dwordx4 v[18:19], v[54:57], off
	global_store_dwordx4 v[18:19], v[14:17], off offset:512
	v_xor_b32_e32 v73, 0x8000, v73
	v_xor_b32_e32 v74, 0x8000, v74
	s_cbranch_vccz .LBB0_2019
	s_mul_hi_i32 s42, s40, 0x2aaaaaab
	s_lshr_b32 s43, s42, 31
	s_ashr_i32 s42, s42, 3
	s_add_i32 s42, s42, s43
	s_mul_i32 s43, s42, 0xffffe800
	s_add_i32 s44, s27, s43
	s_ashr_i32 s45, s44, 31
	v_lshl_add_u64 v[22:23], s[44:45], 2, v[68:69]
	v_add_co_u32_e32 v20, vcc, s30, v22
	v_lshl_add_u64 v[18:19], v[22:23], 0, s[0:1]
	s_nop 0
	v_addc_co_u32_e32 v21, vcc, 0, v23, vcc
	v_add_co_u32_e32 v24, vcc, s34, v22
	global_load_dwordx4 v[14:17], v[22:23], off offset:16
	global_load_dwordx4 v[34:37], v[22:23], off
	v_addc_co_u32_e32 v25, vcc, 0, v23, vcc
	global_load_dwordx4 v[38:41], v[20:21], off
	s_nop 0
	global_load_dwordx4 v[18:21], v[18:19], off offset:16
	s_mul_hi_i32 s43, s42, 0x300
	global_load_dwordx4 v[42:45], v[24:25], off
	v_add_co_u32_e32 v24, vcc, s35, v22
	s_mul_i32 s44, s42, 0x300
	s_nop 0
	v_addc_co_u32_e32 v25, vcc, 0, v23, vcc
	global_load_dwordx4 v[46:49], v[24:25], off
	v_add_co_u32_e32 v24, vcc, s36, v22
	s_mulk_i32 s42, 0xfd00
	s_nop 0
	v_addc_co_u32_e32 v25, vcc, 0, v23, vcc
	global_load_dwordx4 v[50:53], v[24:25], off
	v_lshl_add_u64 v[24:25], v[22:23], 0, s[2:3]
	global_load_dwordx4 v[30:33], v[24:25], off offset:16
	v_lshl_add_u64 v[24:25], v[22:23], 0, s[8:9]
	global_load_dwordx4 v[26:29], v[24:25], off offset:16
	v_lshl_add_u64 v[22:23], v[22:23], 0, s[10:11]
	global_load_dwordx4 v[22:25], v[22:23], off offset:16
.LBB0_2003:
	s_waitcnt vmcnt(13)
	ds_write_b128 v73, v[2:5] offset:512
	s_waitcnt vmcnt(12)
	ds_write_b128 v73, v[6:9] offset:8704
	s_and_saveexec_b64 s[12:13], s[4:5]
	ds_write_b128 v74, v[10:13]
	s_or_b64 exec, exec, s[12:13]
	s_add_i32 s38, s40, s26
	s_cmpk_gt_i32 s38, 0x77ff
	s_cselect_b64 s[12:13], -1, 0
	s_cmpk_lt_i32 s38, 0x7800
	s_mov_b64 s[14:15], -1
	s_cbranch_scc1 .LBB0_2007
	s_add_i32 s39, s37, s29
	s_mov_b64 s[14:15], 0
